# speedup vs baseline: 1.1452x; 1.0082x over previous
; template <int MF, int NF>
; __device__ __forceinline__ void gemm_issue_first(int zz, const u16* __restrict__ Wt, int ldw, const u16* __restrict__ Act, int lda,
;                                                  char* shm) {
;   constexpr int TA = 32 * MF, TB = 64 * NF, NLD = (TA + TB) / 64, NLA = TA / 64;
;   const int tid = TIDX, wid = tid >> 6, lane = tid & 63;
;   const int sb = lane * 16;
;   const int swz = sb ^ (((sb >> 9) & 1) << 5);
;   const int rr = swz >> 6, cc = (swz & 63) >> 1;
;   const unsigned voffA = (unsigned)(((wid >> 1) * 16 + rr) * ldw + (wid & 1) * 32 + cc);
;   const unsigned voffB = (unsigned)(((wid >> 1) * 16 + rr) * lda + (wid & 1) * 32 + cc);
; #pragma unroll
;   for (int i = 0; i < NLD; ++i) {
;     const u16* src = (i < NLA) ? (Wt + (long)(i * 64) * ldw + voffA) : (Act + (long)((i - NLA) * 64) * lda + voffB);
;     __builtin_amdgcn_global_load_lds((const unsigned*)src, (unsigned*)(shm + (i * 8 + wid) * 1024), 16, 0, 0);
;   }
; template <int EPI>
; __device__ __forceinline__ void gemm_phase(int zz, const u16* __restrict__ Wt, const u16* __restrict__ Act, int K, int lda, int nColTiles,
;                            u16* __restrict__ Out, int ldo, int nvalid, char* shm) {
;   const int tid = TIDX, wid = tid >> 6, lane = tid & 63, wr = wid >> 2, wc = wid & 3, fr = lane & 15, fq = lane >> 4;
;   const int nT = NTOK / 256;
;   const int ntiles = nT * nColTiles;
;   int tile = virt_id();
;   __syncthreads();
;   if (tile < ntiles) {
;     int gidx = tile / (8 * nColTiles), rem = tile % (8 * nColTiles);
;     int pm = gidx * 8 + (rem & 7), pn = rem >> 3;
;     gemm_issue_first<8, 4>(zz, Wt + (long)(pn * 256) * K, K, Act + (long)(pm * 256) * lda, lda, shm);
;   }
.Lprio_sw:
	v_add_u32_e32 v144, 0x2000, v131
	v_lshl_add_u64 v[4:5], s[6:7], 0, v[2:3]
	s_mov_b32 m0, s4
	s_mov_b64 s[6:7], 0x20000
	v_readfirstlane_b32 s4, v144
	v_add_u32_e32 v145, 0x4000, v131
	global_load_lds_dwordx4 v[6:7], off
	v_lshl_add_u64 v[8:9], v[6:7], 0, s[6:7]
	s_mov_b32 m0, s4
	s_mov_b64 s[8:9], 0x40000
	v_readfirstlane_b32 s4, v145
	v_add_u32_e32 v146, 0x6000, v131
	global_load_lds_dwordx4 v[8:9], off
	v_lshl_add_u64 v[8:9], v[6:7], 0, s[8:9]
	s_mov_b32 m0, s4
	s_mov_b64 s[10:11], 0x60000
	v_readfirstlane_b32 s4, v146
	v_add_u32_e32 v147, 0x8000, v131
	global_load_lds_dwordx4 v[8:9], off
	v_lshl_add_u64 v[6:7], v[6:7], 0, s[10:11]
	s_mov_b32 m0, s4
	v_readfirstlane_b32 s4, v147
	v_add_u32_e32 v148, 0xa000, v131
	global_load_lds_dwordx4 v[6:7], off
	s_mov_b32 m0, s4
	v_readfirstlane_b32 s4, v148
	v_add_u32_e32 v149, 0xc000, v131
	global_load_lds_dwordx4 v[4:5], off
	v_lshl_add_u64 v[6:7], v[4:5], 0, s[6:7]
	s_mov_b32 m0, s4
	v_readfirstlane_b32 s4, v149
	v_add_u32_e32 v150, 0xe000, v131
	global_load_lds_dwordx4 v[6:7], off
	v_lshl_add_u64 v[6:7], v[4:5], 0, s[8:9]
	s_mov_b32 m0, s4
	v_readfirstlane_b32 s4, v150
	global_load_lds_dwordx4 v[6:7], off
	v_lshl_add_u64 v[4:5], v[4:5], 0, s[10:11]
	s_mov_b32 m0, s4
	v_and_b32_e32 v0, 48, v34
	global_load_lds_dwordx4 v[4:5], off
	v_lshlrev_b32_e32 v4, 6, v34
	v_and_b32_e32 v5, 0x3c0, v4
	v_lshlrev_b32_e32 v7, 2, v34
	v_lshl_add_u64 v[132:133], s[66:67], 0, v[2:3]
	v_lshl_add_u64 v[134:135], s[2:3], 0, v[2:3]
	v_ashrrev_i32_e32 v2, 2, v34
	s_movk_i32 s4, 0xffc0
	v_or_b32_e32 v6, v5, v0
	v_and_b32_e32 v7, 32, v7
	v_and_b32_e32 v152, 0xffffc000, v4
	v_lshlrev_b32_e32 v4, 13, v10
	v_and_or_b32 v155, v2, s4, v0
	s_mov_b32 s4, 0x10000
	v_bitop3_b32 v151, v5, v7, v0 bitop3:0x36
	v_and_b32_e32 v153, 0x6000, v4
	v_bitop3_b32 v4, v6, s4, v7 bitop3:0xde
	v_lshlrev_b32_e32 v0, 10, v12
	s_movk_i32 s4, 0xc000
	v_lshlrev_b32_e32 v2, 8, v34
	v_and_or_b32 v0, v0, s4, v11
	v_and_b32_e32 v2, 0x3c00, v2
	v_or3_b32 v0, v0, v2, v13
	v_or_b32_e32 v5, 0x10000, v153
	v_lshlrev_b64 v[2:3], 1, v[0:1]
	v_and_b32_e32 v154, 0xcf, v34
	v_mov_b32_e32 v179, v2
	v_lshl_add_u64 v[136:137], s[2:3], 0, v[2:3]
	v_lshl_add_u64 v[138:139], s[66:67], 0, v[2:3]
	v_add_u32_e32 v0, v4, v152
	v_add_u32_e32 v156, v5, v151
	s_waitcnt vmcnt(0)
	s_branch .LBB0_223

; #define WAIT_V0() asm volatile("s_waitcnt vmcnt(0)" ::: "memory")
; template <int MF, int NF>
; __device__ __forceinline__ void gemm_main(int zz, f32x4 (&acc)[MF][NF], const u16* __restrict__ Wt, int ldw,
;                                           const u16* __restrict__ Act, int lda, int K, char* shm) {
;     ...
;   WAIT_V0();
;   __syncthreads();
; template <int EPI>
; __device__ __forceinline__ void gemm_phase(int zz, const u16* __restrict__ Wt, const u16* __restrict__ Act, int K, int lda, int nColTiles,
;                            u16* __restrict__ Out, int ldo, int nvalid, char* shm) {
;     ...
;   for (; tile < ntiles; tile += gridDim.x) {
;     int gidx = tile / (8 * nColTiles), rem = tile % (8 * nColTiles);
;     int pm = gidx * 8 + (rem & 7), pn = rem >> 3;
;     int t0 = pm * 256, c0 = pn * 256;
;     f32x4 acc[8][4];
; #pragma unroll
;     for (int m = 0; m < 8; ++m)
; #pragma unroll
;       for (int n = 0; n < 4; ++n) acc[m][n] = f32x4{0.f, 0.f, 0.f, 0.f};
;     gemm_main<8, 4>(zz, acc, Wt + (long)c0 * K, K, Act + (long)t0 * lda, lda, K, shm);
.LBB0_223:
	s_mul_hi_i32 s2, s15, 0x2e8ba2e9
	s_lshr_b32 s3, s2, 31
	s_ashr_i32 s2, s2, 5
	s_add_i32 s2, s2, s3
	s_mul_i32 s3, s2, 0xb0
	s_sub_i32 s3, s15, s3
	s_lshl_b32 s4, s3, 8
	s_lshl_b32 s3, s3, 5
	s_lshl_b32 s7, s2, 11
	s_and_b32 s2, s3, 0xffffff00
	s_ashr_i32 s3, s2, 31
	s_and_b32 s6, s4, 0x700
	s_lshl_b64 s[4:5], s[2:3], 11
	s_add_u32 s36, s40, s4
	s_addc_u32 s37, s41, s5
	s_add_u32 s36, s36, 0x80
	s_addc_u32 s37, s37, 0
	s_or_b32 s4, s7, s6
	s_waitcnt vmcnt(8)
	s_ashr_i32 s5, s4, 31
	s_lshl_b64 s[6:7], s[4:5], 11
	v_mov_b32_e32 v2, 0
	s_add_u32 s38, s66, s6
	s_addc_u32 s39, s67, s7
	s_add_u32 s38, s38, 0x80
	s_addc_u32 s39, s39, 0
	s_mov_b32 s3, 0
	s_mov_b64 s[6:7], 0
	v_mov_b32_e32 v3, v2
	v_mov_b32_e32 v4, v2
	v_mov_b32_e32 v5, v2
	v_mov_b32_e32 v6, v2
	v_mov_b32_e32 v7, v2
	v_mov_b32_e32 v8, v2
	v_mov_b32_e32 v9, v2
	v_mov_b32_e32 v10, v2
	v_mov_b32_e32 v11, v2
	v_mov_b32_e32 v12, v2
	v_mov_b32_e32 v13, v2
	v_mov_b32_e32 v14, v2
	v_mov_b32_e32 v15, v2
	v_mov_b32_e32 v16, v2
	v_mov_b32_e32 v17, v2
	v_mov_b32_e32 v18, v2
	v_mov_b32_e32 v19, v2
	v_mov_b32_e32 v20, v2
	v_mov_b32_e32 v21, v2
	v_mov_b32_e32 v22, v2
	v_mov_b32_e32 v23, v2
	v_mov_b32_e32 v24, v2
	v_mov_b32_e32 v25, v2
	v_mov_b32_e32 v26, v2
	v_mov_b32_e32 v27, v2
	v_mov_b32_e32 v28, v2
	v_mov_b32_e32 v29, v2
	v_mov_b32_e32 v30, v2
	v_mov_b32_e32 v31, v2
	v_mov_b32_e32 v32, v2
	v_mov_b32_e32 v33, v2
	v_mov_b32_e32 v34, v2
	v_mov_b32_e32 v35, v2
	v_mov_b32_e32 v36, v2
	v_mov_b32_e32 v37, v2
	v_mov_b32_e32 v38, v2
	v_mov_b32_e32 v39, v2
	v_mov_b32_e32 v40, v2
	v_mov_b32_e32 v41, v2
	v_mov_b32_e32 v42, v2
	v_mov_b32_e32 v43, v2
	v_mov_b32_e32 v44, v2
	v_mov_b32_e32 v45, v2
	v_mov_b32_e32 v46, v2
	v_mov_b32_e32 v47, v2
	v_mov_b32_e32 v48, v2
	v_mov_b32_e32 v49, v2
	v_mov_b32_e32 v50, v2
	v_mov_b32_e32 v51, v2
	v_mov_b32_e32 v52, v2
	v_mov_b32_e32 v53, v2
	v_mov_b32_e32 v54, v2
	v_mov_b32_e32 v55, v2
	v_mov_b32_e32 v56, v2
	v_mov_b32_e32 v57, v2
	v_mov_b32_e32 v58, v2
	v_mov_b32_e32 v59, v2
	v_mov_b32_e32 v60, v2
	v_mov_b32_e32 v61, v2
	v_mov_b32_e32 v62, v2
	v_mov_b32_e32 v63, v2
	v_mov_b32_e32 v64, v2
	v_mov_b32_e32 v65, v2
	v_mov_b32_e32 v66, v2
	v_mov_b32_e32 v67, v2
	v_mov_b32_e32 v68, v2
	v_mov_b32_e32 v69, v2
	v_mov_b32_e32 v70, v2
	v_mov_b32_e32 v71, v2
	v_mov_b32_e32 v72, v2
	v_mov_b32_e32 v73, v2
	v_mov_b32_e32 v74, v2
	v_mov_b32_e32 v75, v2
	v_mov_b32_e32 v76, v2
	v_mov_b32_e32 v77, v2
	v_mov_b32_e32 v78, v2
	v_mov_b32_e32 v79, v2
	v_mov_b32_e32 v80, v2
	v_mov_b32_e32 v81, v2
	v_mov_b32_e32 v82, v2
	v_mov_b32_e32 v83, v2
	v_mov_b32_e32 v84, v2
	v_mov_b32_e32 v85, v2
	v_mov_b32_e32 v86, v2
	v_mov_b32_e32 v87, v2
	v_mov_b32_e32 v88, v2
	v_mov_b32_e32 v89, v2
	v_mov_b32_e32 v90, v2
	v_mov_b32_e32 v91, v2
	v_mov_b32_e32 v92, v2
	v_mov_b32_e32 v93, v2
	v_mov_b32_e32 v94, v2
	v_mov_b32_e32 v95, v2
	v_mov_b32_e32 v96, v2
	v_mov_b32_e32 v97, v2
	v_mov_b32_e32 v98, v2
	v_mov_b32_e32 v99, v2
	v_mov_b32_e32 v100, v2
	v_mov_b32_e32 v101, v2
	v_mov_b32_e32 v102, v2
	v_mov_b32_e32 v103, v2
	v_mov_b32_e32 v104, v2
	v_mov_b32_e32 v105, v2
	v_mov_b32_e32 v106, v2
	v_mov_b32_e32 v107, v2
	v_mov_b32_e32 v108, v2
	v_mov_b32_e32 v109, v2
	v_mov_b32_e32 v110, v2
	v_mov_b32_e32 v111, v2
	v_mov_b32_e32 v112, v2
	v_mov_b32_e32 v113, v2
	v_mov_b32_e32 v114, v2
	v_mov_b32_e32 v115, v2
	v_mov_b32_e32 v116, v2
	v_mov_b32_e32 v117, v2
	v_mov_b32_e32 v118, v2
	v_mov_b32_e32 v119, v2
	v_mov_b32_e32 v120, v2
	v_mov_b32_e32 v121, v2
	v_mov_b32_e32 v122, v2
	v_mov_b32_e32 v123, v2
	v_mov_b32_e32 v124, v2
	v_mov_b32_e32 v125, v2
	v_mov_b32_e32 v126, v2
	v_mov_b32_e32 v127, v2
	v_mov_b32_e32 v128, v2
	v_mov_b32_e32 v129, v2
	s_waitcnt vmcnt(8) lgkmcnt(0)
	s_barrier

; template <int MF, int NF>
; __device__ __forceinline__ void gemm_issue_first(int zz, const u16* __restrict__ Wt, int ldw, const u16* __restrict__ Act, int lda,
;                                                  char* shm) {
;   constexpr int TA = 32 * MF, TB = 64 * NF, NLD = (TA + TB) / 64, NLA = TA / 64;
;   const int tid = TIDX, wid = tid >> 6, lane = tid & 63;
;   const int sb = lane * 16;
;   const int swz = sb ^ (((sb >> 9) & 1) << 5);
;   const int rr = swz >> 6, cc = (swz & 63) >> 1;
;   const unsigned voffA = (unsigned)(((wid >> 1) * 16 + rr) * ldw + (wid & 1) * 32 + cc);
;   const unsigned voffB = (unsigned)(((wid >> 1) * 16 + rr) * lda + (wid & 1) * 32 + cc);
; #pragma unroll
;   for (int i = 0; i < NLD; ++i) {
;     const u16* src = (i < NLA) ? (Wt + (long)(i * 64) * ldw + voffA) : (Act + (long)((i - NLA) * 64) * lda + voffB);
;     __builtin_amdgcn_global_load_lds((const unsigned*)src, (unsigned*)(shm + (i * 8 + wid) * 1024), 16, 0, 0);
;   }
; template <int EPI>
; __device__ __forceinline__ void gemm_phase(int zz, const u16* __restrict__ Wt, const u16* __restrict__ Act, int K, int lda, int nColTiles,
;                            u16* __restrict__ Out, int ldo, int nvalid, char* shm) {
;   const int tid = TIDX, wid = tid >> 6, lane = tid & 63, wr = wid >> 2, wc = wid & 3, fr = lane & 15, fq = lane >> 4;
;   const int nT = NTOK / 256;
;   const int ntiles = nT * nColTiles;
;   int tile = virt_id();
;   __syncthreads();
;   if (tile < ntiles) {
;     int gidx = tile / (8 * nColTiles), rem = tile % (8 * nColTiles);
;     int pm = gidx * 8 + (rem & 7), pn = rem >> 3;
;     gemm_issue_first<8, 4>(zz, Wt + (long)(pn * 256) * K, K, Act + (long)(pm * 256) * lda, lda, shm);
;   }
.LBB0_250:
	v_writelane_b32 v254, s44, 19
	v_writelane_b32 v254, s45, 25
	s_lshl_b32 s34, s8, 7
	s_cmp_ge_i32 s31, s34
	s_waitcnt vmcnt(0)
	s_barrier
	s_cbranch_scc1 .LBB0_260
	s_lshl_b32 s35, s8, 3
	v_cvt_f32_ubyte0_e32 v0, s35
	v_rcp_iflag_f32_e32 v0, v0
	s_sub_i32 s8, 0, s35
	s_abs_i32 s3, s31
	v_readlane_b32 s2, v253, 30
	v_mul_f32_e32 v0, 0x4f7ffffe, v0
	v_cvt_u32_f32_e32 v0, v0
	v_add_u32_e32 v10, s2, v180
	s_ashr_i32 s2, s31, 31
	v_and_b32_e32 v2, 32, v10
	v_readfirstlane_b32 s9, v0
	s_mul_i32 s8, s8, s9
	s_mul_hi_u32 s8, s9, s8
	s_add_i32 s36, s9, s8
	s_mul_hi_u32 s8, s3, s36
	s_mul_i32 s9, s8, s35
	s_sub_i32 s3, s3, s9
	s_add_i32 s10, s8, 1
	s_sub_i32 s9, s3, s35
	s_cmp_ge_u32 s3, s35
	s_cselect_b32 s8, s10, s8
	s_cselect_b32 s3, s9, s3
	s_add_i32 s9, s8, 1
	s_cmp_ge_u32 s3, s35
	s_cselect_b32 s3, s9, s8
	s_xor_b32 s3, s3, s2
	s_sub_i32 s8, s3, s2
	s_mul_i32 s2, s8, s35
	s_sub_i32 s9, s31, s2
	s_lshl_b32 s2, s9, 5
	s_and_b32 s2, s2, 0xffffff00
	s_mul_hi_i32 s3, s2, s29
	s_mul_i32 s2, s2, s29
	s_lshl_b64 s[2:3], s[2:3], 1
	v_lshlrev_b32_e32 v0, 4, v10
	s_add_u32 s2, s6, s2
	v_bitop3_b32 v0, v0, v2, 48 bitop3:0x6c
	s_addc_u32 s3, s7, s3
	s_lshl_b32 s9, s9, 8
	v_lshrrev_b32_e32 v3, 2, v10
	v_lshrrev_b32_e32 v12, 1, v0
	v_ashrrev_i32_e32 v0, 3, v10
	s_lshl_b32 s8, s8, 11
	s_and_b32 s9, s9, 0x700
	v_ashrrev_i32_e32 v11, 6, v10
	v_bfi_b32 v0, 15, v3, v0
	s_or_b32 s8, s9, s8
	v_mul_lo_u32 v13, s29, v0
	v_lshlrev_b32_e32 v0, 5, v11
	s_mul_hi_i32 s9, s8, s29
	s_mul_i32 s8, s8, s29
	v_and_b32_e32 v14, 32, v0
	s_lshl_b64 s[8:9], s[8:9], 1
	v_or3_b32 v0, v13, v12, v14
	s_add_u32 s8, s4, s8
	v_lshlrev_b32_e32 v131, 10, v11
	v_lshlrev_b64 v[2:3], 1, v[0:1]
	s_addc_u32 s9, s5, s9
	v_lshl_add_u64 v[6:7], s[2:3], 0, v[2:3]
	v_readfirstlane_b32 s2, v131
	v_readfirstlane_b32 s44, v131
	s_cmp_ge_u32 s44, 0x1000
	s_cbranch_scc0 .Lprio_pl
	s_setprio 1
.Lprio_pl:
	v_add_u32_e32 v140, 0x2000, v131
	v_lshl_add_u64 v[4:5], s[8:9], 0, v[2:3]
	s_mov_b32 m0, s2
	s_lshl_b32 s2, s29, 7
	s_mov_b32 s3, s77
	v_readfirstlane_b32 s8, v140
	v_add_u32_e32 v141, 0x4000, v131
	global_load_lds_dwordx4 v[6:7], off
	v_lshl_add_u64 v[8:9], v[6:7], 0, s[2:3]
	s_mov_b32 m0, s8
	v_readfirstlane_b32 s8, v141
	global_load_lds_dwordx4 v[8:9], off
	s_lshl_b32 s76, s29, 8
	s_mov_b32 m0, s8
	s_mul_i32 s8, s29, 0xc0
	v_add_u32_e32 v142, 0x6000, v131
	v_lshl_add_u64 v[8:9], v[6:7], 0, s[76:77]
	s_lshl_b32 s76, s8, 1
	v_readfirstlane_b32 s9, v142
	v_add_u32_e32 v143, 0x8000, v131
	global_load_lds_dwordx4 v[8:9], off
	v_lshl_add_u64 v[6:7], v[6:7], 0, s[76:77]
	s_mov_b32 m0, s9
	v_readfirstlane_b32 s9, v143
	v_add_u32_e32 v144, 0xa000, v131
	global_load_lds_dwordx4 v[6:7], off
	s_mov_b32 m0, s9
	v_readfirstlane_b32 s9, v144
	v_add_u32_e32 v145, 0xc000, v131
	global_load_lds_dwordx4 v[4:5], off
	v_lshl_add_u64 v[4:5], v[4:5], 0, s[2:3]
	s_mov_b32 m0, s9
	v_readfirstlane_b32 s9, v145
	v_add_u32_e32 v146, 0xe000, v131
	global_load_lds_dwordx4 v[4:5], off
	v_lshl_add_u64 v[4:5], v[4:5], 0, s[2:3]
	s_mov_b32 m0, s9
	v_readfirstlane_b32 s9, v146
	global_load_lds_dwordx4 v[4:5], off
	v_lshl_add_u64 v[4:5], v[4:5], 0, s[2:3]
	s_mov_b32 m0, s9
	s_lshr_b32 s37, s29, 6
	global_load_lds_dwordx4 v[4:5], off
	s_lshl_b32 s9, s29, 6
	v_lshlrev_b32_e32 v4, 6, v10
	v_lshlrev_b32_e32 v6, 2, v10
	s_add_i32 s37, s37, -1
	v_and_b32_e32 v0, 48, v10
	v_and_b32_e32 v5, 0x3c0, v4
	v_and_b32_e32 v6, 32, v6
	s_add_u32 s38, s6, 0x80
	v_bitop3_b32 v147, v5, v6, v0 bitop3:0x36
	v_lshlrev_b32_e32 v0, 13, v11
	v_lshl_add_u64 v[132:133], s[4:5], 0, v[2:3]
	v_lshl_add_u64 v[134:135], s[6:7], 0, v[2:3]
	v_lshlrev_b32_e32 v2, 1, v10
	s_addc_u32 s39, s7, 0
	s_lshl_b32 s40, s29, 1
	v_and_b32_e32 v149, 0x6000, v0
	v_ashrrev_i32_e32 v0, 1, v10
	v_and_b32_e32 v2, 0x60, v2
	s_movk_i32 s10, 0xff80
	s_add_u32 s41, s4, 0x80
	v_and_or_b32 v150, v0, s10, v2
	v_add3_u32 v0, v12, v13, v14
	s_addc_u32 s42, s5, 0
	s_lshl_b32 s76, s9, 1
	s_mov_b32 s80, s20
	v_and_b32_e32 v148, 0xffffc000, v4
	v_and_b32_e32 v151, 0xcf, v10
	v_lshlrev_b64 v[136:137], 1, v[0:1]
	s_mov_b64 s[78:79], s[76:77]
	s_lshl_b32 s4, s2, 1
	s_lshl_b32 s6, s8, 1
	s_mov_b32 s45, 0
	s_branch .LBB0_253

; #define WAIT_V0() asm volatile("s_waitcnt vmcnt(0)" ::: "memory")
; template <int MF, int NF>
; __device__ __forceinline__ void gemm_main(int zz, f32x4 (&acc)[MF][NF], const u16* __restrict__ Wt, int ldw,
;                                           const u16* __restrict__ Act, int lda, int K, char* shm) {
;     ...
;   WAIT_V0();
;   __syncthreads();
; template <int EPI>
; __device__ __forceinline__ void gemm_phase(int zz, const u16* __restrict__ Wt, const u16* __restrict__ Act, int K, int lda, int nColTiles,
;                            u16* __restrict__ Out, int ldo, int nvalid, char* shm) {
;     ...
;   for (; tile < ntiles; tile += gridDim.x) {
;     int gidx = tile / (8 * nColTiles), rem = tile % (8 * nColTiles);
;     int pm = gidx * 8 + (rem & 7), pn = rem >> 3;
;     int t0 = pm * 256, c0 = pn * 256;
;     f32x4 acc[8][4];
; #pragma unroll
;     for (int m = 0; m < 8; ++m)
; #pragma unroll
;       for (int n = 0; n < 4; ++n) acc[m][n] = f32x4{0.f, 0.f, 0.f, 0.f};
;     gemm_main<8, 4>(zz, acc, Wt + (long)c0 * K, K, Act + (long)t0 * lda, lda, K, shm);
.LBB0_253:
	s_abs_i32 s7, s31
	s_mul_hi_u32 s8, s7, s36
	s_mul_i32 s9, s8, s35
	s_sub_i32 s7, s7, s9
	s_ashr_i32 s5, s31, 31
	s_add_i32 s9, s8, 1
	s_sub_i32 s10, s7, s35
	s_cmp_ge_u32 s7, s35
	s_cselect_b32 s8, s9, s8
	s_cselect_b32 s7, s10, s7
	s_add_i32 s9, s8, 1
	s_cmp_ge_u32 s7, s35
	s_cselect_b32 s7, s9, s8
	s_xor_b32 s7, s7, s5
	s_sub_i32 s43, s7, s5
	s_mul_i32 s8, s43, s35
	s_sub_i32 s8, s31, s8
	s_lshl_b32 s9, s8, 8
	s_lshl_b32 s8, s8, 5
	s_and_b32 s77, s8, 0xffffff00
	s_and_b32 s76, s9, 0x700
	s_ashr_i32 s8, s77, 31
	s_mul_i32 s10, s40, s77
	s_mul_hi_i32 s9, s40, s77
	s_add_u32 s12, s38, s10
	s_addc_u32 s13, s39, s9
	s_lshl_b32 s9, s77, 1
	s_or_b32 s10, s9, 0x80
	s_mul_i32 s8, s29, s8
	s_mul_hi_u32 s11, s29, s10
	s_add_i32 s11, s11, s8
	s_mul_i32 s10, s29, s10
	s_add_u32 s14, s38, s10
	s_addc_u32 s15, s39, s11
	s_or_b32 s10, s9, 0x100
	s_mul_hi_u32 s11, s29, s10
	s_add_i32 s11, s11, s8
	s_mul_i32 s10, s29, s10
	s_add_u32 s16, s38, s10
	s_addc_u32 s17, s39, s11
	s_or_b32 s9, s9, 0x180
	s_mul_hi_u32 s10, s29, s9
	s_add_i32 s10, s10, s8
	s_mul_i32 s8, s29, s9
	s_add_u32 s18, s38, s8
	s_addc_u32 s19, s39, s10
	s_lshl_b32 s7, s7, 11
	s_or_b32 s7, s7, s76
	s_lshl_b32 s5, s5, 11
	s_sub_i32 s5, s7, s5
	s_ashr_i32 s7, s5, 31
	s_mul_i32 s9, s40, s5
	s_mul_hi_i32 s8, s40, s5
	s_add_u32 s20, s41, s9
	s_addc_u32 s21, s42, s8
	s_lshl_b32 s5, s5, 1
	s_or_b32 s8, s5, 0x100
	s_mul_i32 s7, s29, s7
	s_mul_hi_u32 s9, s29, s8
	s_add_i32 s9, s9, s7
	s_mul_i32 s8, s29, s8
	s_add_u32 s22, s41, s8
	s_addc_u32 s23, s42, s9
	s_or_b32 s8, s5, 0x180
	s_mul_hi_u32 s9, s29, s8
	s_add_i32 s9, s9, s7
	s_mul_i32 s8, s29, s8
	s_add_u32 s24, s41, s8
	s_addc_u32 s25, s42, s9
	s_bitset1_b32 s5, 7
	s_mul_hi_u32 s8, s29, s5
	s_nop 0
	s_add_i32 s8, s8, s7
	s_mul_i32 s5, s29, s5
	s_add_u32 s26, s41, s5
	v_mov_b32_e32 v2, 0
	s_addc_u32 s27, s42, s8
	s_mov_b32 s5, 0
	s_mov_b32 s7, 0
	v_mov_b32_e32 v3, v2
	v_mov_b32_e32 v4, v2
	v_mov_b32_e32 v5, v2
	v_mov_b32_e32 v6, v2
	v_mov_b32_e32 v7, v2
	v_mov_b32_e32 v8, v2
	v_mov_b32_e32 v9, v2
	v_mov_b32_e32 v10, v2
	v_mov_b32_e32 v11, v2
	v_mov_b32_e32 v12, v2
	v_mov_b32_e32 v13, v2
	v_mov_b32_e32 v14, v2
	v_mov_b32_e32 v15, v2
	v_mov_b32_e32 v16, v2
	v_mov_b32_e32 v17, v2
	v_mov_b32_e32 v18, v2
	v_mov_b32_e32 v19, v2
	v_mov_b32_e32 v20, v2
	v_mov_b32_e32 v21, v2
	v_mov_b32_e32 v22, v2
	v_mov_b32_e32 v23, v2
	v_mov_b32_e32 v24, v2
	v_mov_b32_e32 v25, v2
	v_mov_b32_e32 v26, v2
	v_mov_b32_e32 v27, v2
	v_mov_b32_e32 v28, v2
	v_mov_b32_e32 v29, v2
	v_mov_b32_e32 v30, v2
	v_mov_b32_e32 v31, v2
	v_mov_b32_e32 v32, v2
	v_mov_b32_e32 v33, v2
	v_mov_b32_e32 v34, v2
	v_mov_b32_e32 v35, v2
	v_mov_b32_e32 v36, v2
	v_mov_b32_e32 v37, v2
	v_mov_b32_e32 v38, v2
	v_mov_b32_e32 v39, v2
	v_mov_b32_e32 v40, v2
	v_mov_b32_e32 v41, v2
	v_mov_b32_e32 v42, v2
	v_mov_b32_e32 v43, v2
	v_mov_b32_e32 v44, v2
	v_mov_b32_e32 v45, v2
	v_mov_b32_e32 v46, v2
	v_mov_b32_e32 v47, v2
	v_mov_b32_e32 v48, v2
	v_mov_b32_e32 v49, v2
	v_mov_b32_e32 v50, v2
	v_mov_b32_e32 v51, v2
	v_mov_b32_e32 v52, v2
	v_mov_b32_e32 v53, v2
	v_mov_b32_e32 v54, v2
	v_mov_b32_e32 v55, v2
	v_mov_b32_e32 v56, v2
	v_mov_b32_e32 v57, v2
	v_mov_b32_e32 v58, v2
	v_mov_b32_e32 v59, v2
	v_mov_b32_e32 v60, v2
	v_mov_b32_e32 v61, v2
	v_mov_b32_e32 v62, v2
	v_mov_b32_e32 v63, v2
	v_mov_b32_e32 v64, v2
	v_mov_b32_e32 v65, v2
	v_mov_b32_e32 v66, v2
	v_mov_b32_e32 v67, v2
	v_mov_b32_e32 v68, v2
	v_mov_b32_e32 v69, v2
	v_mov_b32_e32 v70, v2
	v_mov_b32_e32 v71, v2
	v_mov_b32_e32 v72, v2
	v_mov_b32_e32 v73, v2
	v_mov_b32_e32 v74, v2
	v_mov_b32_e32 v75, v2
	v_mov_b32_e32 v76, v2
	v_mov_b32_e32 v77, v2
	v_mov_b32_e32 v78, v2
	v_mov_b32_e32 v79, v2
	v_mov_b32_e32 v80, v2
	v_mov_b32_e32 v81, v2
	v_mov_b32_e32 v82, v2
	v_mov_b32_e32 v83, v2
	v_mov_b32_e32 v84, v2
	v_mov_b32_e32 v85, v2
	v_mov_b32_e32 v86, v2
	v_mov_b32_e32 v87, v2
	v_mov_b32_e32 v88, v2
	v_mov_b32_e32 v89, v2
	v_mov_b32_e32 v90, v2
	v_mov_b32_e32 v91, v2
	v_mov_b32_e32 v92, v2
	v_mov_b32_e32 v93, v2
	v_mov_b32_e32 v94, v2
	v_mov_b32_e32 v95, v2
	v_mov_b32_e32 v96, v2
	v_mov_b32_e32 v97, v2
	v_mov_b32_e32 v98, v2
	v_mov_b32_e32 v99, v2
	v_mov_b32_e32 v100, v2
	v_mov_b32_e32 v101, v2
	v_mov_b32_e32 v102, v2
	v_mov_b32_e32 v103, v2
	v_mov_b32_e32 v104, v2
	v_mov_b32_e32 v105, v2
	v_mov_b32_e32 v106, v2
	v_mov_b32_e32 v107, v2
	v_mov_b32_e32 v108, v2
	v_mov_b32_e32 v109, v2
	v_mov_b32_e32 v110, v2
	v_mov_b32_e32 v111, v2
	v_mov_b32_e32 v112, v2
	v_mov_b32_e32 v113, v2
	v_mov_b32_e32 v114, v2
	v_mov_b32_e32 v115, v2
	v_mov_b32_e32 v116, v2
	v_mov_b32_e32 v117, v2
	v_mov_b32_e32 v118, v2
	v_mov_b32_e32 v119, v2
	v_mov_b32_e32 v120, v2
	v_mov_b32_e32 v121, v2
	v_mov_b32_e32 v122, v2
	v_mov_b32_e32 v123, v2
	v_mov_b32_e32 v124, v2
	v_mov_b32_e32 v125, v2
	v_mov_b32_e32 v126, v2
	v_mov_b32_e32 v127, v2
	v_mov_b32_e32 v128, v2
	v_mov_b32_e32 v129, v2
	s_waitcnt lgkmcnt(0)
	s_cmp_eq_u32 s45, 1
	s_cbranch_scc1 .Lpl_b16
	s_waitcnt vmcnt(0)
	s_branch .Lpl_bar
.Lpl_b16:
	s_waitcnt vmcnt(16)
.Lpl_bar:
	s_barrier
; template <int MF, int NF>
; __device__ __forceinline__ void gemm_main(int zz, f32x4 (&acc)[MF][NF], const u16* __restrict__ Wt, int ldw,
;                                           const u16* __restrict__ Act, int lda, int K, char* shm) {
;     ...
;   for (int t = 0; t < nt; ++t) {
;     const int cur = t & 1;
;     if (t + 1 < nt) {
; #pragma unroll
;       for (int i = 0; i < NLD; ++i) {
;         const u16* src = (i < NLA) ? (Wt + (long)(i * 64) * ldw + (t + 1) * 64 + voffA)
;                                    : (Act + (long)((i - NLA) * 64) * lda + (t + 1) * 64 + voffB);
;         __builtin_amdgcn_global_load_lds((const unsigned*)src, (unsigned*)(shm + (cur ^ 1) * STAGE_B + (i * 8 + wid) * 1024), 16, 0, 0);
;       }
;     }
;     const char* sbase = shm + cur * STAGE_B;
;     {
;       constexpr int D = (NF >= 4) ? 3 : ((MF >= 12) ? 6 : 4), RING = D + 1, NSTEP = 2 * MF;
;       bf16x8 Bf[2][NF], Ar[RING];
; #pragma unroll
;       for (int n = 0; n < NF; ++n) Bf[0][n] = *(const bf16x8*)(sbase + boff + (n * 2 + 0) * 1024);
; #pragma unroll
;       for (int j = 0; j < D; ++j) Ar[j % RING] = *(const bf16x8*)(sbase + aoff + ((j % MF) * 2 + (j / MF)) * 1024);
;       __builtin_amdgcn_sched_barrier(0);
;       __builtin_amdgcn_s_setprio(1);
; #pragma unroll
;       for (int i = 0; i < NSTEP; ++i) {
;         const int ks = i / MF, m = i % MF;
;         const int j = i + D;
;         if (j < NSTEP) {
;           const int ksj = j / MF, mj = j % MF;
;           if (mj == 0) {
; #pragma unroll
;             for (int n = 0; n < NF; ++n) Bf[ksj][n] = *(const bf16x8*)(sbase + boff + (n * 2 + ksj) * 1024);
;           }
;           Ar[j % RING] = *(const bf16x8*)(sbase + aoff + (mj * 2 + ksj) * 1024);
;         }
; #pragma unroll
;         for (int n = 0; n < NF; ++n) acc[m][n] = __builtin_amdgcn_mfma_f32_16x16x32_bf16(Ar[i % RING], Bf[ks][n], acc[m][n], 0, 0, 0);
;         __builtin_amdgcn_sched_barrier(0);
;       }
.LBB0_254:
	s_and_b32 s8, s5, 0x10000
	s_xor_b32 s9, s8, 0x10000
	s_add_i32 s9, s9, s44
	s_mov_b32 m0, s9
	s_add_i32 s7, s7, 1
	v_or_b32_e32 v0, s8, v147
	v_add_u32_e32 v138, v0, v149
	v_add_u32_e32 v0, v0, v148
	ds_read_b128 v[168:171], v0
	ds_read_b128 v[152:155], v138 offset:32768
	ds_read_b128 v[156:159], v138 offset:34816
	ds_read_b128 v[160:163], v138 offset:36864
	ds_read_b128 v[164:167], v138 offset:38912
	ds_read_b128 v[172:175], v0 offset:2048
	ds_read_b128 v[176:179], v0 offset:4096
	s_nop 0
	s_waitcnt lgkmcnt(5)
	v_mfma_f32_16x16x32_bf16 v[126:129], v[168:171], v[152:155], v[126:129]
	ds_read_b128 v[192:195], v0 offset:6144
	s_waitcnt lgkmcnt(5)
	v_mfma_f32_16x16x32_bf16 v[122:125], v[168:171], v[156:159], v[122:125]
	global_load_lds_dwordx4 v136, s[12:13]
	s_waitcnt lgkmcnt(4)
	v_mfma_f32_16x16x32_bf16 v[118:121], v[168:171], v[160:163], v[118:121]
	s_addk_i32 m0, 0x2000
	s_waitcnt lgkmcnt(3)
	v_mfma_f32_16x16x32_bf16 v[114:117], v[168:171], v[164:167], v[114:117]
	s_waitcnt lgkmcnt(2)
	v_mfma_f32_16x16x32_bf16 v[110:113], v[172:175], v[152:155], v[110:113]
	ds_read_b128 v[168:171], v0 offset:8192
	v_mfma_f32_16x16x32_bf16 v[106:109], v[172:175], v[156:159], v[106:109]
	global_load_lds_dwordx4 v136, s[14:15]
	v_mfma_f32_16x16x32_bf16 v[102:105], v[172:175], v[160:163], v[102:105]
	s_addk_i32 m0, 0x2000
	v_mfma_f32_16x16x32_bf16 v[98:101], v[172:175], v[164:167], v[98:101]
	s_waitcnt lgkmcnt(2)
	v_mfma_f32_16x16x32_bf16 v[94:97], v[176:179], v[152:155], v[94:97]
	ds_read_b128 v[172:175], v0 offset:10240
	v_mfma_f32_16x16x32_bf16 v[90:93], v[176:179], v[156:159], v[90:93]
	global_load_lds_dwordx4 v136, s[16:17]
	v_mfma_f32_16x16x32_bf16 v[86:89], v[176:179], v[160:163], v[86:89]
	s_addk_i32 m0, 0x2000
	v_mfma_f32_16x16x32_bf16 v[82:85], v[176:179], v[164:167], v[82:85]
	s_waitcnt lgkmcnt(2)
	v_mfma_f32_16x16x32_bf16 v[78:81], v[192:195], v[152:155], v[78:81]
	ds_read_b128 v[176:179], v0 offset:12288
	v_mfma_f32_16x16x32_bf16 v[74:77], v[192:195], v[156:159], v[74:77]
	global_load_lds_dwordx4 v136, s[18:19]
	v_mfma_f32_16x16x32_bf16 v[70:73], v[192:195], v[160:163], v[70:73]
	s_addk_i32 m0, 0x2000
	v_mfma_f32_16x16x32_bf16 v[66:69], v[192:195], v[164:167], v[66:69]
	s_waitcnt lgkmcnt(2)
	v_mfma_f32_16x16x32_bf16 v[62:65], v[168:171], v[152:155], v[62:65]
	ds_read_b128 v[192:195], v0 offset:14336
	v_mfma_f32_16x16x32_bf16 v[58:61], v[168:171], v[156:159], v[58:61]
	global_load_lds_dwordx4 v136, s[20:21]
	v_mfma_f32_16x16x32_bf16 v[54:57], v[168:171], v[160:163], v[54:57]
	s_addk_i32 m0, 0x2000
	v_mfma_f32_16x16x32_bf16 v[50:53], v[168:171], v[164:167], v[50:53]
	ds_read_b128 v[168:171], v138 offset:33792
	ds_read_b128 v[196:199], v138 offset:35840
	ds_read_b128 v[200:203], v138 offset:37888
	ds_read_b128 v[204:207], v138 offset:39936
	ds_read_b128 v[208:211], v0 offset:1024
	s_waitcnt lgkmcnt(7)
	v_mfma_f32_16x16x32_bf16 v[46:49], v[172:175], v[152:155], v[46:49]
	v_mfma_f32_16x16x32_bf16 v[42:45], v[172:175], v[156:159], v[42:45]
	global_load_lds_dwordx4 v136, s[26:27]
	v_mfma_f32_16x16x32_bf16 v[38:41], v[172:175], v[160:163], v[38:41]
	s_addk_i32 m0, 0x2000
	v_mfma_f32_16x16x32_bf16 v[34:37], v[172:175], v[164:167], v[34:37]
	s_waitcnt lgkmcnt(6)
	v_mfma_f32_16x16x32_bf16 v[30:33], v[176:179], v[152:155], v[30:33]
	ds_read_b128 v[172:175], v0 offset:3072
	v_mfma_f32_16x16x32_bf16 v[26:29], v[176:179], v[156:159], v[26:29]
	global_load_lds_dwordx4 v136, s[22:23]
	v_mfma_f32_16x16x32_bf16 v[22:25], v[176:179], v[160:163], v[22:25]
	s_addk_i32 m0, 0x2000
	v_mfma_f32_16x16x32_bf16 v[18:21], v[176:179], v[164:167], v[18:21]
	s_waitcnt lgkmcnt(6)
	v_mfma_f32_16x16x32_bf16 v[14:17], v[192:195], v[152:155], v[14:17]
	ds_read_b128 v[152:155], v0 offset:5120
	v_mfma_f32_16x16x32_bf16 v[10:13], v[192:195], v[156:159], v[10:13]
	global_load_lds_dwordx4 v136, s[24:25]
	v_mfma_f32_16x16x32_bf16 v[6:9], v[192:195], v[160:163], v[6:9]
	v_mfma_f32_16x16x32_bf16 v[2:5], v[192:195], v[164:167], v[2:5]
	s_waitcnt lgkmcnt(2)
	v_mfma_f32_16x16x32_bf16 v[126:129], v[208:211], v[168:171], v[126:129]
	ds_read_b128 v[156:159], v0 offset:7168
	v_mfma_f32_16x16x32_bf16 v[122:125], v[208:211], v[196:199], v[122:125]
	v_mfma_f32_16x16x32_bf16 v[118:121], v[208:211], v[200:203], v[118:121]
	v_mfma_f32_16x16x32_bf16 v[114:117], v[208:211], v[204:207], v[114:117]
	s_waitcnt lgkmcnt(2)
	v_mfma_f32_16x16x32_bf16 v[110:113], v[172:175], v[168:171], v[110:113]
	ds_read_b128 v[160:163], v0 offset:9216
	v_mfma_f32_16x16x32_bf16 v[106:109], v[172:175], v[196:199], v[106:109]
	v_mfma_f32_16x16x32_bf16 v[102:105], v[172:175], v[200:203], v[102:105]
	v_mfma_f32_16x16x32_bf16 v[98:101], v[172:175], v[204:207], v[98:101]
	s_waitcnt lgkmcnt(2)
	v_mfma_f32_16x16x32_bf16 v[94:97], v[152:155], v[168:171], v[94:97]
	ds_read_b128 v[164:167], v0 offset:11264
	v_mfma_f32_16x16x32_bf16 v[90:93], v[152:155], v[196:199], v[90:93]
	v_mfma_f32_16x16x32_bf16 v[86:89], v[152:155], v[200:203], v[86:89]
	v_mfma_f32_16x16x32_bf16 v[82:85], v[152:155], v[204:207], v[82:85]
	s_waitcnt lgkmcnt(2)
	v_mfma_f32_16x16x32_bf16 v[78:81], v[156:159], v[168:171], v[78:81]
	ds_read_b128 v[152:155], v0 offset:13312
	v_mfma_f32_16x16x32_bf16 v[74:77], v[156:159], v[196:199], v[74:77]
	v_mfma_f32_16x16x32_bf16 v[70:73], v[156:159], v[200:203], v[70:73]
	v_mfma_f32_16x16x32_bf16 v[66:69], v[156:159], v[204:207], v[66:69]
	s_waitcnt lgkmcnt(2)
	v_mfma_f32_16x16x32_bf16 v[62:65], v[160:163], v[168:171], v[62:65]
	ds_read_b128 v[156:159], v0 offset:15360
	v_mfma_f32_16x16x32_bf16 v[58:61], v[160:163], v[196:199], v[58:61]
	v_mfma_f32_16x16x32_bf16 v[54:57], v[160:163], v[200:203], v[54:57]
	v_mfma_f32_16x16x32_bf16 v[50:53], v[160:163], v[204:207], v[50:53]
	s_waitcnt lgkmcnt(2)
; template <int MF, int NF>
; __device__ __forceinline__ void gemm_main(int zz, f32x4 (&acc)[MF][NF], const u16* __restrict__ Wt, int ldw,
;                                           const u16* __restrict__ Act, int lda, int K, char* shm) {
;     ...
;   for (int t = 0; t < nt; ++t) {
;     const int cur = t & 1;
;     if (t + 1 < nt) {
; #pragma unroll
;       for (int i = 0; i < NLD; ++i) {
;         const u16* src = (i < NLA) ? (Wt + (long)(i * 64) * ldw + (t + 1) * 64 + voffA)
;                                    : (Act + (long)((i - NLA) * 64) * lda + (t + 1) * 64 + voffB);
;         __builtin_amdgcn_global_load_lds((const unsigned*)src, (unsigned*)(shm + (cur ^ 1) * STAGE_B + (i * 8 + wid) * 1024), 16, 0, 0);
;       }
;     }
;     const char* sbase = shm + cur * STAGE_B;
;     {
;       constexpr int D = (NF >= 4) ? 3 : ((MF >= 12) ? 6 : 4), RING = D + 1, NSTEP = 2 * MF;
;       bf16x8 Bf[2][NF], Ar[RING];
; #pragma unroll
;       for (int n = 0; n < NF; ++n) Bf[0][n] = *(const bf16x8*)(sbase + boff + (n * 2 + 0) * 1024);
; #pragma unroll
;       for (int j = 0; j < D; ++j) Ar[j % RING] = *(const bf16x8*)(sbase + aoff + ((j % MF) * 2 + (j / MF)) * 1024);
;       __builtin_amdgcn_sched_barrier(0);
;       __builtin_amdgcn_s_setprio(1);
; #pragma unroll
;       for (int i = 0; i < NSTEP; ++i) {
;         const int ks = i / MF, m = i % MF;
;         const int j = i + D;
;         if (j < NSTEP) {
;           const int ksj = j / MF, mj = j % MF;
;           if (mj == 0) {
; #pragma unroll
;             for (int n = 0; n < NF; ++n) Bf[ksj][n] = *(const bf16x8*)(sbase + boff + (n * 2 + ksj) * 1024);
;           }
;           Ar[j % RING] = *(const bf16x8*)(sbase + aoff + (mj * 2 + ksj) * 1024);
;         }
; #pragma unroll
;         for (int n = 0; n < NF; ++n) acc[m][n] = __builtin_amdgcn_mfma_f32_16x16x32_bf16(Ar[i % RING], Bf[ks][n], acc[m][n], 0, 0, 0);
;         __builtin_amdgcn_sched_barrier(0);
;       }
;       __builtin_amdgcn_s_setprio(0);
;     }
	v_mfma_f32_16x16x32_bf16 v[46:49], v[164:167], v[168:171], v[46:49]
	v_mfma_f32_16x16x32_bf16 v[42:45], v[164:167], v[196:199], v[42:45]
	v_mfma_f32_16x16x32_bf16 v[38:41], v[164:167], v[200:203], v[38:41]
	v_mfma_f32_16x16x32_bf16 v[34:37], v[164:167], v[204:207], v[34:37]
	s_waitcnt lgkmcnt(1)
	v_mfma_f32_16x16x32_bf16 v[30:33], v[152:155], v[168:171], v[30:33]
	v_mfma_f32_16x16x32_bf16 v[26:29], v[152:155], v[196:199], v[26:29]
	v_mfma_f32_16x16x32_bf16 v[22:25], v[152:155], v[200:203], v[22:25]
	v_mfma_f32_16x16x32_bf16 v[18:21], v[152:155], v[204:207], v[18:21]
	s_waitcnt lgkmcnt(0)
	v_mfma_f32_16x16x32_bf16 v[14:17], v[156:159], v[168:171], v[14:17]
	v_mfma_f32_16x16x32_bf16 v[10:13], v[156:159], v[196:199], v[10:13]
	v_mfma_f32_16x16x32_bf16 v[6:9], v[156:159], v[200:203], v[6:9]
	v_mfma_f32_16x16x32_bf16 v[2:5], v[156:159], v[204:207], v[2:5]
	s_nop 0
	s_add_i32 s5, s5, 0x10000
	s_add_u32 s12, s12, 0x80
	s_addc_u32 s13, s13, 0
	s_add_u32 s14, s14, 0x80
	s_addc_u32 s15, s15, 0
	s_add_u32 s16, s16, 0x80
	s_addc_u32 s17, s17, 0
	s_add_u32 s18, s18, 0x80
	s_addc_u32 s19, s19, 0
	s_add_u32 s20, s20, 0x80
	s_addc_u32 s21, s21, 0
	s_add_u32 s22, s22, 0x80
	s_addc_u32 s23, s23, 0
	s_add_u32 s24, s24, 0x80
	s_addc_u32 s25, s25, 0
	s_waitcnt vmcnt(0)
	s_add_u32 s26, s26, 0x80
	s_addc_u32 s27, s27, 0
	s_cmp_lg_u32 s37, s7
	s_waitcnt vmcnt(0)
	s_barrier
	s_cbranch_scc1 .LBB0_254
	s_lshl_b32 s5, s37, 16
	s_and_b32 s5, s5, 0x10000
	v_or_b32_e32 v0, s5, v147
	v_add_u32_e32 v138, v0, v149
	ds_read_b128 v[152:155], v138 offset:32768
	ds_read_b128 v[156:159], v138 offset:34816
	ds_read_b128 v[160:163], v138 offset:36864
	ds_read_b128 v[164:167], v138 offset:38912
	v_add_u32_e32 v0, v0, v148
	ds_read_b128 v[168:171], v0
	ds_read_b128 v[172:175], v0 offset:2048
	ds_read_b128 v[176:179], v0 offset:4096
	s_setprio 1
	s_waitcnt lgkmcnt(2)
	v_mfma_f32_16x16x32_bf16 v[126:129], v[168:171], v[152:155], v[126:129]
	ds_read_b128 v[192:195], v0 offset:6144
	v_mfma_f32_16x16x32_bf16 v[122:125], v[168:171], v[156:159], v[122:125]
	v_mfma_f32_16x16x32_bf16 v[118:121], v[168:171], v[160:163], v[118:121]
	v_mfma_f32_16x16x32_bf16 v[114:117], v[168:171], v[164:167], v[114:117]
	s_waitcnt lgkmcnt(2)
	v_mfma_f32_16x16x32_bf16 v[168:171], v[172:175], v[160:163], v[102:105]
	s_nop 2
	ds_read_b128 v[102:105], v0 offset:8192
	v_mfma_f32_16x16x32_bf16 v[110:113], v[172:175], v[152:155], v[110:113]
	v_mfma_f32_16x16x32_bf16 v[106:109], v[172:175], v[156:159], v[106:109]
	v_mfma_f32_16x16x32_bf16 v[172:175], v[172:175], v[164:167], v[98:101]
	s_nop 2
	ds_read_b128 v[98:101], v0 offset:10240
	s_waitcnt lgkmcnt(3)
	v_mfma_f32_16x16x32_bf16 v[94:97], v[176:179], v[152:155], v[94:97]
	v_mfma_f32_16x16x32_bf16 v[90:93], v[176:179], v[156:159], v[90:93]
	v_mfma_f32_16x16x32_bf16 v[86:89], v[176:179], v[160:163], v[86:89]
	v_mfma_f32_16x16x32_bf16 v[82:85], v[176:179], v[164:167], v[82:85]
	s_waitcnt lgkmcnt(2)
	v_mfma_f32_16x16x32_bf16 v[196:199], v[192:195], v[160:163], v[70:73]
	s_nop 2
	ds_read_b128 v[70:73], v0 offset:12288
	v_mfma_f32_16x16x32_bf16 v[78:81], v[192:195], v[152:155], v[78:81]
	v_mfma_f32_16x16x32_bf16 v[176:179], v[192:195], v[156:159], v[74:77]
	v_mfma_f32_16x16x32_bf16 v[192:195], v[192:195], v[164:167], v[66:69]
	s_nop 2
	ds_read_b128 v[66:69], v0 offset:14336
	s_waitcnt lgkmcnt(3)
	v_mfma_f32_16x16x32_bf16 v[62:65], v[102:105], v[152:155], v[62:65]
	v_mfma_f32_16x16x32_bf16 v[58:61], v[102:105], v[156:159], v[58:61]
	v_mfma_f32_16x16x32_bf16 v[54:57], v[102:105], v[160:163], v[54:57]
	v_mfma_f32_16x16x32_bf16 v[200:203], v[102:105], v[164:167], v[50:53]
	ds_read_b128 v[212:215], v138 offset:33792
	ds_read_b128 v[216:219], v138 offset:35840
	s_waitcnt lgkmcnt(4)
	v_mfma_f32_16x16x32_bf16 v[220:223], v[98:101], v[160:163], v[38:41]
	ds_read_b128 v[224:227], v138 offset:37888
	ds_read_b128 v[228:231], v138 offset:39936
	s_nop 0
	ds_read_b128 v[38:41], v0 offset:1024
	v_mfma_f32_16x16x32_bf16 v[204:207], v[98:101], v[152:155], v[46:49]
	v_mfma_f32_16x16x32_bf16 v[208:211], v[98:101], v[156:159], v[42:45]
	v_mfma_f32_16x16x32_bf16 v[232:235], v[98:101], v[164:167], v[34:37]
	s_waitcnt lgkmcnt(6)
	v_mfma_f32_16x16x32_bf16 v[236:239], v[70:73], v[156:159], v[26:29]
	s_nop 2
	ds_read_b128 v[26:29], v0 offset:3072
	v_mfma_f32_16x16x32_bf16 v[30:33], v[70:73], v[152:155], v[30:33]
	v_mfma_f32_16x16x32_bf16 v[22:25], v[70:73], v[160:163], v[22:25]
	v_mfma_f32_16x16x32_bf16 v[240:243], v[70:73], v[164:167], v[18:21]
	s_waitcnt lgkmcnt(6)
	v_mfma_f32_16x16x32_bf16 v[156:159], v[66:69], v[156:159], v[10:13]
	s_nop 2
	ds_read_b128 v[10:13], v0 offset:5120
	v_mfma_f32_16x16x32_bf16 v[152:155], v[66:69], v[152:155], v[14:17]
	v_mfma_f32_16x16x32_bf16 v[160:163], v[66:69], v[160:163], v[6:9]
	v_mfma_f32_16x16x32_bf16 v[164:167], v[66:69], v[164:167], v[2:5]
	s_nop 0
	ds_read_b128 v[14:17], v0 offset:7168
	s_waitcnt lgkmcnt(3)
	v_mfma_f32_16x16x32_bf16 v[98:101], v[38:41], v[212:215], v[126:129]
	v_mfma_f32_16x16x32_bf16 v[66:69], v[38:41], v[216:219], v[122:125]
	v_mfma_f32_16x16x32_bf16 v[34:37], v[38:41], v[224:227], v[118:121]
	v_mfma_f32_16x16x32_bf16 v[2:5], v[38:41], v[228:231], v[114:117]
	ds_read_b128 v[18:21], v0 offset:9216
	s_waitcnt lgkmcnt(3)
	v_mfma_f32_16x16x32_bf16 v[102:105], v[26:29], v[212:215], v[110:113]
	v_mfma_f32_16x16x32_bf16 v[70:73], v[26:29], v[216:219], v[106:109]
	v_mfma_f32_16x16x32_bf16 v[38:41], v[26:29], v[224:227], v[168:171]
	v_mfma_f32_16x16x32_bf16 v[6:9], v[26:29], v[228:231], v[172:175]
	ds_read_b128 v[26:29], v0 offset:11264
	s_waitcnt lgkmcnt(3)
; #define WAIT_V0() asm volatile("s_waitcnt vmcnt(0)" ::: "memory")
; template <int MF, int NF>
; __device__ __forceinline__ void gemm_main(int zz, f32x4 (&acc)[MF][NF], const u16* __restrict__ Wt, int ldw,
;                                           const u16* __restrict__ Act, int lda, int K, char* shm) {
;     ...
;       }
;       __builtin_amdgcn_s_setprio(0);
;     }
;     WAIT_V0();
;     __syncthreads();
;   }
; template <int EPI>
; __device__ __forceinline__ void gemm_phase(int zz, const u16* __restrict__ Wt, const u16* __restrict__ Act, int K, int lda, int nColTiles,
;                            u16* __restrict__ Out, int ldo, int nvalid, char* shm) {
;     ...
;     {
;       int nx = tile + gridDim.x;
;       if (nx < ntiles) {
;         int g2 = nx / (8 * nColTiles), r2 = nx % (8 * nColTiles);
;         int pm2 = g2 * 8 + (r2 & 7), pn2 = r2 >> 3;
;         gemm_issue_first<8, 4>(zz, Wt + (long)(pn2 * 256) * K, K, Act + (long)(pm2 * 256) * lda, lda, shm);
;       }
;     }
	v_mfma_f32_16x16x32_bf16 v[106:109], v[10:13], v[212:215], v[94:97]
	v_mfma_f32_16x16x32_bf16 v[74:77], v[10:13], v[216:219], v[90:93]
	v_mfma_f32_16x16x32_bf16 v[42:45], v[10:13], v[224:227], v[86:89]
	v_mfma_f32_16x16x32_bf16 v[10:13], v[10:13], v[228:231], v[82:85]
	ds_read_b128 v[94:97], v0 offset:13312
	s_waitcnt lgkmcnt(3)
	v_mfma_f32_16x16x32_bf16 v[110:113], v[14:17], v[212:215], v[78:81]
	v_mfma_f32_16x16x32_bf16 v[78:81], v[14:17], v[216:219], v[176:179]
	v_mfma_f32_16x16x32_bf16 v[46:49], v[14:17], v[224:227], v[196:199]
	v_mfma_f32_16x16x32_bf16 v[14:17], v[14:17], v[228:231], v[192:195]
	s_waitcnt lgkmcnt(2)
	v_mfma_f32_16x16x32_bf16 v[114:117], v[18:21], v[212:215], v[62:65]
	ds_read_b128 v[168:171], v0 offset:15360
	v_mfma_f32_16x16x32_bf16 v[82:85], v[18:21], v[216:219], v[58:61]
	v_mfma_f32_16x16x32_bf16 v[50:53], v[18:21], v[224:227], v[54:57]
	v_mfma_f32_16x16x32_bf16 v[18:21], v[18:21], v[228:231], v[200:203]
	s_waitcnt lgkmcnt(2)
	v_mfma_f32_16x16x32_bf16 v[122:125], v[26:29], v[212:215], v[204:207]
	v_mfma_f32_16x16x32_bf16 v[90:93], v[26:29], v[216:219], v[208:211]
	v_mfma_f32_16x16x32_bf16 v[58:61], v[26:29], v[224:227], v[220:223]
	v_mfma_f32_16x16x32_bf16 v[26:29], v[26:29], v[228:231], v[232:235]
	s_waitcnt lgkmcnt(1)
	v_mfma_f32_16x16x32_bf16 v[118:121], v[94:97], v[212:215], v[30:33]
	v_mfma_f32_16x16x32_bf16 v[86:89], v[94:97], v[216:219], v[236:239]
	v_mfma_f32_16x16x32_bf16 v[54:57], v[94:97], v[224:227], v[22:25]
	v_mfma_f32_16x16x32_bf16 v[22:25], v[94:97], v[228:231], v[240:243]
	s_waitcnt lgkmcnt(0)
	v_mfma_f32_16x16x32_bf16 v[126:129], v[168:171], v[212:215], v[152:155]
	v_mfma_f32_16x16x32_bf16 v[94:97], v[168:171], v[216:219], v[156:159]
	v_mfma_f32_16x16x32_bf16 v[62:65], v[168:171], v[224:227], v[160:163]
	v_mfma_f32_16x16x32_bf16 v[30:33], v[168:171], v[228:231], v[164:167]
	s_setprio 0
	s_add_i32 s31, s31, s30
	s_waitcnt vmcnt(0)
	s_cmp_ge_i32 s31, s34
	s_cselect_b64 s[12:13], -1, 0
	s_and_b64 vcc, exec, s[12:13]
	s_barrier
	s_cbranch_vccnz .LBB0_257
	s_abs_i32 s7, s31
	s_mul_hi_u32 s8, s7, s36
	s_mul_i32 s9, s8, s35
	s_sub_i32 s7, s7, s9
	s_ashr_i32 s5, s31, 31
	s_add_i32 s9, s8, 1
	s_sub_i32 s10, s7, s35
	s_cmp_ge_u32 s7, s35
	s_cselect_b32 s8, s9, s8
	s_cselect_b32 s7, s10, s7
	s_add_i32 s9, s8, 1
	s_cmp_ge_u32 s7, s35
	s_cselect_b32 s7, s9, s8
	s_xor_b32 s7, s7, s5
	s_sub_i32 s5, s7, s5
	s_mul_i32 s7, s5, s35
	s_sub_i32 s7, s31, s7
	s_lshl_b32 s8, s7, 5
	s_lshl_b32 s7, s7, 8
	s_lshl_b32 s5, s5, 11
	s_and_b32 s7, s7, 0x700
	s_and_b32 s8, s8, 0xffffff00
	s_or_b32 s5, s7, s5
	s_mul_hi_i32 s9, s8, s29
	s_mul_i32 s8, s8, s29
	s_mul_hi_i32 s11, s5, s29
	s_mul_i32 s10, s5, s29
	v_readfirstlane_b32 s5, v131
	v_lshl_add_u64 v[152:153], s[8:9], 1, v[134:135]
	s_mov_b32 m0, s5
	s_mov_b64 s[8:9], s[78:79]
	v_readfirstlane_b32 s5, v140
	global_load_lds_dwordx4 v[152:153], off
	v_lshl_add_u64 v[154:155], v[152:153], 0, s[8:9]
	s_mov_b32 m0, s5
	s_mov_b32 s5, s79
	global_load_lds_dwordx4 v[154:155], off
	v_lshl_add_u64 v[154:155], v[152:153], 0, s[4:5]
	v_readfirstlane_b32 s5, v141
	s_mov_b32 m0, s5
	s_mov_b32 s7, s79
	v_readfirstlane_b32 s5, v142
	global_load_lds_dwordx4 v[154:155], off
	v_lshl_add_u64 v[152:153], v[152:153], 0, s[6:7]
	s_mov_b32 m0, s5
	v_readfirstlane_b32 s5, v143
	v_lshl_add_u64 v[138:139], s[10:11], 1, v[132:133]
	global_load_lds_dwordx4 v[152:153], off
	s_mov_b32 m0, s5
	v_readfirstlane_b32 s5, v144
	global_load_lds_dwordx4 v[138:139], off
	v_lshl_add_u64 v[138:139], v[138:139], 0, s[2:3]
	s_mov_b32 m0, s5
	v_readfirstlane_b32 s5, v145
	global_load_lds_dwordx4 v[138:139], off
	v_lshl_add_u64 v[138:139], v[138:139], 0, s[2:3]
	s_mov_b32 m0, s5
	v_readfirstlane_b32 s5, v146
	global_load_lds_dwordx4 v[138:139], off
	v_lshl_add_u64 v[138:139], v[138:139], 0, s[2:3]
	s_mov_b32 m0, s5
	s_nop 0
	global_load_lds_dwordx4 v[138:139], off
	v_add_u32_e32 v138, s77, v150
	v_cmp_gt_i32_e32 vcc, s28, v138
	s_mov_b32 s45, 0
	s_and_saveexec_b64 s[14:15], vcc
	s_cbranch_execz .LBB0_252
	s_branch .LBB0_258
.LBB0_257:
	v_add_u32_e32 v138, s77, v150
	v_cmp_gt_i32_e32 vcc, s28, v138
	s_mov_b32 s45, 0
	s_and_saveexec_b64 s[14:15], vcc
	s_cbranch_execz .LBB0_252
; template <int EPI>
; __device__ __forceinline__ void gemm_phase(int zz, const u16* __restrict__ Wt, const u16* __restrict__ Act, int K, int lda, int nColTiles,
;                            u16* __restrict__ Out, int ldo, int nvalid, char* shm) {
;     ...
; #pragma unroll
;     for (int n = 0; n < 4; ++n) {
;       int token = t0 + wc * 64 + n * 16 + fr;
;       if (EPI == 0) {
;         int col0 = c0 + wr * 128 + fq * 32;
;         if (col0 < nvalid) {
;           u16* dst = Out + (long)token * ldo + col0;
; #pragma unroll
;           for (int mm = 0; mm < 4; ++mm) {
;             uint4 v;
;             v.x = pack2(acc[2 * mm][n][0], acc[2 * mm][n][1]);
;             v.y = pack2(acc[2 * mm][n][2], acc[2 * mm][n][3]);
;             v.z = pack2(acc[2 * mm + 1][n][0], acc[2 * mm + 1][n][1]);
;             v.w = pack2(acc[2 * mm + 1][n][2], acc[2 * mm + 1][n][3]);
;             *(uint4*)(dst + mm * 8) = v;
;           }
;         }
.LBB0_258:
	s_mov_b32 s45, 1
	s_lshl_b32 s5, s43, 11
	s_or_b32 s5, s76, s5
	v_and_b32_e32 v160, 0x60, v150
	v_lshrrev_b32_e32 v161, 2, v160
	v_sub_u32_e32 v160, v161, v160
	v_add_u32_e32 v138, v138, v160
	v_ashrrev_i32_e32 v139, 31, v138
	v_or_b32_e32 v0, s5, v151
	v_lshl_add_u64 v[138:139], v[138:139], 1, s[0:1]
	v_mad_i64_i32 v[152:153], s[8:9], v0, s28, 0
	v_lshl_add_u64 v[152:153], v[152:153], 1, v[138:139]
	v_or_b32_e32 v162, 16, v0
	v_mad_i64_i32 v[154:155], s[8:9], v162, s28, 0
	v_lshl_add_u64 v[154:155], v[154:155], 1, v[138:139]
	v_or_b32_e32 v162, 32, v0
	v_mad_i64_i32 v[156:157], s[8:9], v162, s28, 0
	v_lshl_add_u64 v[156:157], v[156:157], 1, v[138:139]
	v_or_b32_e32 v162, 48, v0
	v_mad_i64_i32 v[158:159], s[8:9], v162, s28, 0
	v_lshl_add_u64 v[158:159], v[158:159], 1, v[138:139]
	v_cvt_pk_bf16_f32 v98, v98, v99
	v_cvt_pk_bf16_f32 v99, v100, v101
	v_cvt_pk_bf16_f32 v100, v102, v103
	v_cvt_pk_bf16_f32 v101, v104, v105
	v_cvt_pk_bf16_f32 v106, v106, v107
	v_cvt_pk_bf16_f32 v107, v108, v109
	v_cvt_pk_bf16_f32 v108, v110, v111
	v_cvt_pk_bf16_f32 v109, v112, v113
	v_cvt_pk_bf16_f32 v114, v114, v115
	v_cvt_pk_bf16_f32 v115, v116, v117
	v_cvt_pk_bf16_f32 v116, v122, v123
	v_cvt_pk_bf16_f32 v117, v124, v125
	v_cvt_pk_bf16_f32 v118, v118, v119
	v_cvt_pk_bf16_f32 v119, v120, v121
	v_cvt_pk_bf16_f32 v120, v126, v127
	v_cvt_pk_bf16_f32 v121, v128, v129
	s_nop 1
	v_permlane32_swap_b32_e32 v98, v114
	v_permlane32_swap_b32_e32 v99, v115
	v_permlane32_swap_b32_e32 v100, v116
	v_permlane32_swap_b32_e32 v101, v117
	v_permlane32_swap_b32_e32 v106, v118
	v_permlane32_swap_b32_e32 v107, v119
	v_permlane32_swap_b32_e32 v108, v120
	v_permlane32_swap_b32_e32 v109, v121
	v_permlane16_swap_b32_e32 v98, v106
	v_permlane16_swap_b32_e32 v99, v107
	v_permlane16_swap_b32_e32 v100, v108
	v_permlane16_swap_b32_e32 v101, v109
	v_permlane16_swap_b32_e32 v114, v118
	v_permlane16_swap_b32_e32 v115, v119
	v_permlane16_swap_b32_e32 v116, v120
	v_permlane16_swap_b32_e32 v117, v121
	s_nop 1
	global_store_dwordx4 v[152:153], v[98:101], off
	global_store_dwordx4 v[152:153], v[106:109], off offset:64
	global_store_dwordx4 v[152:153], v[114:117], off offset:128
	global_store_dwordx4 v[152:153], v[118:121], off offset:192
	v_cvt_pk_bf16_f32 v66, v66, v67
	v_cvt_pk_bf16_f32 v67, v68, v69
	v_cvt_pk_bf16_f32 v68, v70, v71
	v_cvt_pk_bf16_f32 v69, v72, v73
	v_cvt_pk_bf16_f32 v74, v74, v75
	v_cvt_pk_bf16_f32 v75, v76, v77
	v_cvt_pk_bf16_f32 v76, v78, v79
	v_cvt_pk_bf16_f32 v77, v80, v81
	v_cvt_pk_bf16_f32 v82, v82, v83
	v_cvt_pk_bf16_f32 v83, v84, v85
	v_cvt_pk_bf16_f32 v84, v90, v91
	v_cvt_pk_bf16_f32 v85, v92, v93
	v_cvt_pk_bf16_f32 v86, v86, v87
	v_cvt_pk_bf16_f32 v87, v88, v89
	v_cvt_pk_bf16_f32 v88, v94, v95
	v_cvt_pk_bf16_f32 v89, v96, v97
	s_nop 1
	v_permlane32_swap_b32_e32 v66, v82
	v_permlane32_swap_b32_e32 v67, v83
	v_permlane32_swap_b32_e32 v68, v84
	v_permlane32_swap_b32_e32 v69, v85
	v_permlane32_swap_b32_e32 v74, v86
	v_permlane32_swap_b32_e32 v75, v87
	v_permlane32_swap_b32_e32 v76, v88
	v_permlane32_swap_b32_e32 v77, v89
	v_permlane16_swap_b32_e32 v66, v74
	v_permlane16_swap_b32_e32 v67, v75
	v_permlane16_swap_b32_e32 v68, v76
	v_permlane16_swap_b32_e32 v69, v77
	v_permlane16_swap_b32_e32 v82, v86
	v_permlane16_swap_b32_e32 v83, v87
	v_permlane16_swap_b32_e32 v84, v88
	v_permlane16_swap_b32_e32 v85, v89
	s_nop 1
	global_store_dwordx4 v[154:155], v[66:69], off
	global_store_dwordx4 v[154:155], v[74:77], off offset:64
	global_store_dwordx4 v[154:155], v[82:85], off offset:128
	global_store_dwordx4 v[154:155], v[86:89], off offset:192
	v_cvt_pk_bf16_f32 v34, v34, v35
	v_cvt_pk_bf16_f32 v35, v36, v37
	v_cvt_pk_bf16_f32 v36, v38, v39
	v_cvt_pk_bf16_f32 v37, v40, v41
	v_cvt_pk_bf16_f32 v42, v42, v43
	v_cvt_pk_bf16_f32 v43, v44, v45
	v_cvt_pk_bf16_f32 v44, v46, v47
	v_cvt_pk_bf16_f32 v45, v48, v49
	v_cvt_pk_bf16_f32 v50, v50, v51
	v_cvt_pk_bf16_f32 v51, v52, v53
	v_cvt_pk_bf16_f32 v52, v58, v59
	v_cvt_pk_bf16_f32 v53, v60, v61
	v_cvt_pk_bf16_f32 v54, v54, v55
	v_cvt_pk_bf16_f32 v55, v56, v57
	v_cvt_pk_bf16_f32 v56, v62, v63
	v_cvt_pk_bf16_f32 v57, v64, v65
	s_nop 1
	v_permlane32_swap_b32_e32 v34, v50
	v_permlane32_swap_b32_e32 v35, v51
	v_permlane32_swap_b32_e32 v36, v52
	v_permlane32_swap_b32_e32 v37, v53
	v_permlane32_swap_b32_e32 v42, v54
	v_permlane32_swap_b32_e32 v43, v55
	v_permlane32_swap_b32_e32 v44, v56
	v_permlane32_swap_b32_e32 v45, v57
	v_permlane16_swap_b32_e32 v34, v42
	v_permlane16_swap_b32_e32 v35, v43
	v_permlane16_swap_b32_e32 v36, v44
	v_permlane16_swap_b32_e32 v37, v45
	v_permlane16_swap_b32_e32 v50, v54
	v_permlane16_swap_b32_e32 v51, v55
	v_permlane16_swap_b32_e32 v52, v56
	v_permlane16_swap_b32_e32 v53, v57
	s_nop 1
	global_store_dwordx4 v[156:157], v[34:37], off
	global_store_dwordx4 v[156:157], v[42:45], off offset:64
	global_store_dwordx4 v[156:157], v[50:53], off offset:128
	global_store_dwordx4 v[156:157], v[54:57], off offset:192
	v_cvt_pk_bf16_f32 v2, v2, v3
	v_cvt_pk_bf16_f32 v3, v4, v5
	v_cvt_pk_bf16_f32 v4, v6, v7
	v_cvt_pk_bf16_f32 v5, v8, v9
	v_cvt_pk_bf16_f32 v10, v10, v11
	v_cvt_pk_bf16_f32 v11, v12, v13
	v_cvt_pk_bf16_f32 v12, v14, v15
	v_cvt_pk_bf16_f32 v13, v16, v17
	v_cvt_pk_bf16_f32 v18, v18, v19
	v_cvt_pk_bf16_f32 v19, v20, v21
	v_cvt_pk_bf16_f32 v20, v26, v27
	v_cvt_pk_bf16_f32 v21, v28, v29
	v_cvt_pk_bf16_f32 v22, v22, v23
	v_cvt_pk_bf16_f32 v23, v24, v25
	v_cvt_pk_bf16_f32 v24, v30, v31
	v_cvt_pk_bf16_f32 v25, v32, v33
	s_nop 1
	v_permlane32_swap_b32_e32 v2, v18
	v_permlane32_swap_b32_e32 v3, v19
	v_permlane32_swap_b32_e32 v4, v20
	v_permlane32_swap_b32_e32 v5, v21
	v_permlane32_swap_b32_e32 v10, v22
	v_permlane32_swap_b32_e32 v11, v23
	v_permlane32_swap_b32_e32 v12, v24
	v_permlane32_swap_b32_e32 v13, v25
	v_permlane16_swap_b32_e32 v2, v10
	v_permlane16_swap_b32_e32 v3, v11
	v_permlane16_swap_b32_e32 v4, v12
	v_permlane16_swap_b32_e32 v5, v13
	v_permlane16_swap_b32_e32 v18, v22
	v_permlane16_swap_b32_e32 v19, v23
	v_permlane16_swap_b32_e32 v20, v24
	v_permlane16_swap_b32_e32 v21, v25
	s_nop 1
	global_store_dwordx4 v[158:159], v[2:5], off
	global_store_dwordx4 v[158:159], v[10:13], off offset:64
	global_store_dwordx4 v[158:159], v[18:21], off offset:128
	global_store_dwordx4 v[158:159], v[22:25], off offset:192
	s_branch .LBB0_252

; __device__ __forceinline__ void run_step(int zz, const Params& p, int s, char* shm) {
;     ...
;     gemm_phase<0>(zz, wt, act, K, K, nct, out, ldo, nvalid, shm);
;   }
;   if (kind == 5) mixer_phase(zz, p, l, j - 5, shm);
;   if (kind == 6) g4_phase(zz, p, shm);
.LBB0_260:
	v_readlane_b32 s44, v254, 19
	v_readlane_b32 s45, v254, 25
	s_setprio 0
	v_readlane_b32 s0, v253, 32
	s_cmp_lt_i32 s0, 6
	s_mov_b64 s[0:1], -1
	s_mov_b64 s[22:23], s[82:83]
	s_mov_b64 s[24:25], s[84:85]
	s_cbranch_scc1 .LBB0_262
	v_readlane_b32 s2, v253, 32
	s_cmp_eq_u32 s2, 6
	s_mov_b64 s[0:1], 0
	s_cselect_b64 s[22:23], -1, 0
